# P0 weight preparation: the 32 per-iteration load/wait/multiply round trips of the norm_pre fold de-serialised (all loads issued, one wait, then the multiplies); on top of the previous best
# speedup vs baseline: 1.0247x; 1.0183x over previous
; #define LAS __attribute__((address_space(3)))
; DI void transpose_w(const float* __restrict__ w, const float* __restrict__ rowscale, bf16_t* __restrict__ out, int K, int N, int bid, int nb, LAS float* tile) {
;     const int tid = threadIdx.x, nkt = K / 64, nnt = N / 32, ntile = nkt * nnt;
;     for (int t0 = bid; t0 < ntile; t0 += 8 * nb) {
;         __syncthreads();
;         float v[8][4];
; #pragma unroll
;         for (int q = 0; q < 8; ++q) { const int t = t0 + q * nb; if (t < ntile) { const int k0 = (t % nkt) * 64, n0 = (t / nkt) * 32;
; #pragma unroll
;             for (int it = 0; it < 4; ++it) { const int i = it * 16 + (tid >> 5), j = tid & 31; v[q][it] = w[(size_t)(k0 + i) * N + n0 + j]; if (rowscale) v[q][it] *= rowscale[k0 + i]; } } }
.LBB0_6:
	s_ashr_i32 s0, s83, 31
	s_lshr_b32 s0, s0, 27
	s_add_i32 s0, s83, s0
	s_lshl_b32 s1, s0, 6
	s_and_b32 s4, s1, 0xfffff800
	s_and_b32 s30, s0, 0xffffffe0
	s_sub_i32 s0, s71, s4
	s_ashr_i32 s31, s30, 31
	v_add_u32_e32 v14, s0, v3
	v_lshl_add_u64 v[16:17], s[30:31], 2, v[12:13]
	v_mad_i64_i32 v[18:19], s[0:1], v14, s82, v[16:17]
	s_barrier
	global_load_dword v6, v[18:19], off
	v_ashrrev_i32_e32 v15, 31, v14
	v_cmp_ne_u32_e64 s[0:1], 1, v22
	s_andn2_b64 vcc, exec, s[18:19]
	v_lshl_add_u64 v[18:19], v[14:15], 2, s[26:27]
	s_cbranch_vccnz .LBB0_8
	global_load_dword v160, v[18:19], off
.LBB0_8:
	v_add_u32_e32 v15, 16, v14
	v_mad_i64_i32 v[52:53], s[2:3], v15, s82, v[16:17]
	global_load_dword v52, v[52:53], off
	s_and_b64 vcc, exec, s[0:1]
	s_cbranch_vccnz .LBB0_10
	global_load_dword v161, v[18:19], off offset:64
.LBB0_10:
	v_add_u32_e32 v15, 32, v14
	v_mad_i64_i32 v[54:55], s[2:3], v15, s82, v[16:17]
	global_load_dword v53, v[54:55], off
	s_and_b64 vcc, exec, s[0:1]
	s_cbranch_vccnz .LBB0_12
	global_load_dword v162, v[18:19], off offset:128
.LBB0_12:
	v_add_u32_e32 v14, 48, v14
	v_mad_i64_i32 v[14:15], s[2:3], v14, s82, v[16:17]
	global_load_dword v54, v[14:15], off
	s_and_b64 vcc, exec, s[0:1]
	s_cbranch_vccnz .LBB0_14
	global_load_dword v163, v[18:19], off offset:192
.LBB0_14:
	s_add_i32 s31, s94, s83
	s_cmpk_lt_i32 s31, 0x1620
	s_cselect_b64 s[2:3], -1, 0
	s_cmpk_gt_i32 s31, 0x161f
	s_cbranch_scc1 .LBB0_23
	s_ashr_i32 s5, s31, 31
	s_lshr_b32 s5, s5, 27
	s_add_i32 s5, s31, s5
	s_and_b32 s6, s5, 0xffffffe0
	s_sub_i32 s5, s31, s6
	v_lshl_or_b32 v16, s5, 6, v3
	s_ashr_i32 s7, s6, 31
	v_lshl_add_u64 v[14:15], s[6:7], 2, v[12:13]
	v_mul_hi_i32_i24_e32 v19, 0x5880, v16
	v_mul_i32_i24_e32 v18, 0x5880, v16
	v_lshl_add_u64 v[18:19], v[14:15], 0, v[18:19]
	global_load_dword v32, v[18:19], off
	v_ashrrev_i32_e32 v17, 31, v16
	s_and_b64 vcc, exec, s[0:1]
	v_lshl_add_u64 v[18:19], v[16:17], 2, s[26:27]
	s_cbranch_vccnz .LBB0_17
	global_load_dword v164, v[18:19], off
.LBB0_17:
	v_add_u32_e32 v17, 16, v16
	v_mul_hi_i32_i24_e32 v57, 0x5880, v17
	v_mul_i32_i24_e32 v56, 0x5880, v17
	v_lshl_add_u64 v[56:57], v[14:15], 0, v[56:57]
	global_load_dword v39, v[56:57], off
	s_and_b64 vcc, exec, s[0:1]
	s_cbranch_vccnz .LBB0_19
	global_load_dword v165, v[18:19], off offset:64
.LBB0_19:
	v_or_b32_e32 v17, 32, v16
	v_mul_hi_i32_i24_e32 v57, 0x5880, v17
	v_mul_i32_i24_e32 v56, 0x5880, v17
	v_lshl_add_u64 v[56:57], v[14:15], 0, v[56:57]
	global_load_dword v46, v[56:57], off
	s_and_b64 vcc, exec, s[0:1]
	s_cbranch_vccnz .LBB0_21
	global_load_dword v166, v[18:19], off offset:128
.LBB0_21:
	v_add_u32_e32 v16, 48, v16
	v_mul_hi_i32_i24_e32 v17, 0x5880, v16
	v_mul_i32_i24_e32 v16, 0x5880, v16
	v_lshl_add_u64 v[14:15], v[14:15], 0, v[16:17]
	global_load_dword v51, v[14:15], off
	s_and_b64 vcc, exec, s[0:1]
	s_cbranch_vccnz .LBB0_23
	global_load_dword v167, v[18:19], off offset:192
.LBB0_23:
	s_sub_i32 s86, 0, s4
	s_add_i32 s84, s76, s83
	s_cmpk_lt_i32 s84, 0x1620
	s_cselect_b64 s[4:5], -1, 0
	s_cmpk_gt_i32 s84, 0x161f
	s_cbranch_scc1 .LBB0_32
	s_ashr_i32 s6, s84, 31
	s_lshr_b32 s6, s6, 27
	s_add_i32 s6, s84, s6
	s_andn2_b32 s6, s6, 31
	s_sub_i32 s7, s84, s6
	v_lshl_or_b32 v16, s7, 6, v3
	s_ashr_i32 s7, s6, 31
	v_lshl_add_u64 v[14:15], s[6:7], 2, v[12:13]
	v_mul_hi_i32_i24_e32 v19, 0x5880, v16
	v_mul_i32_i24_e32 v18, 0x5880, v16
	v_lshl_add_u64 v[18:19], v[14:15], 0, v[18:19]
	global_load_dword v30, v[18:19], off
	v_ashrrev_i32_e32 v17, 31, v16
	s_and_b64 vcc, exec, s[0:1]
	v_lshl_add_u64 v[18:19], v[16:17], 2, s[26:27]
	s_cbranch_vccnz .LBB0_26
	global_load_dword v168, v[18:19], off
.LBB0_26:
	v_add_u32_e32 v17, 16, v16
	v_mul_hi_i32_i24_e32 v57, 0x5880, v17
	v_mul_i32_i24_e32 v56, 0x5880, v17
	v_lshl_add_u64 v[56:57], v[14:15], 0, v[56:57]
	global_load_dword v37, v[56:57], off
	s_and_b64 vcc, exec, s[0:1]
	s_cbranch_vccnz .LBB0_28
	global_load_dword v169, v[18:19], off offset:64
.LBB0_28:
	v_or_b32_e32 v17, 32, v16
	v_mul_hi_i32_i24_e32 v57, 0x5880, v17
	v_mul_i32_i24_e32 v56, 0x5880, v17
	v_lshl_add_u64 v[56:57], v[14:15], 0, v[56:57]
	global_load_dword v44, v[56:57], off
	s_and_b64 vcc, exec, s[0:1]
	s_cbranch_vccnz .LBB0_30
	global_load_dword v170, v[18:19], off offset:128
.LBB0_30:
	v_add_u32_e32 v16, 48, v16
	v_mul_hi_i32_i24_e32 v17, 0x5880, v16
	v_mul_i32_i24_e32 v16, 0x5880, v16
	v_lshl_add_u64 v[14:15], v[14:15], 0, v[16:17]
	global_load_dword v50, v[14:15], off
	s_and_b64 vcc, exec, s[0:1]
	s_cbranch_vccnz .LBB0_32
	global_load_dword v171, v[18:19], off offset:192
.LBB0_32:
	s_add_i32 s85, s77, s83
	s_cmpk_lt_i32 s85, 0x1620
	s_cselect_b64 s[6:7], -1, 0
	s_cmpk_gt_i32 s85, 0x161f
	s_cbranch_scc1 .LBB0_41
	s_ashr_i32 s8, s85, 31
	s_lshr_b32 s8, s8, 27
	s_add_i32 s8, s85, s8
	s_andn2_b32 s8, s8, 31
	s_sub_i32 s9, s85, s8
	v_lshl_or_b32 v16, s9, 6, v3
	s_ashr_i32 s9, s8, 31
	v_lshl_add_u64 v[14:15], s[8:9], 2, v[12:13]
	v_mul_hi_i32_i24_e32 v19, 0x5880, v16
	v_mul_i32_i24_e32 v18, 0x5880, v16
	v_lshl_add_u64 v[18:19], v[14:15], 0, v[18:19]
	global_load_dword v28, v[18:19], off
	v_ashrrev_i32_e32 v17, 31, v16
	s_and_b64 vcc, exec, s[0:1]
	v_lshl_add_u64 v[18:19], v[16:17], 2, s[26:27]
	s_cbranch_vccnz .LBB0_35
	global_load_dword v172, v[18:19], off
.LBB0_35:
	v_add_u32_e32 v17, 16, v16
	v_mul_hi_i32_i24_e32 v57, 0x5880, v17
	v_mul_i32_i24_e32 v56, 0x5880, v17
	v_lshl_add_u64 v[56:57], v[14:15], 0, v[56:57]
	global_load_dword v35, v[56:57], off
	s_and_b64 vcc, exec, s[0:1]
	s_cbranch_vccnz .LBB0_37
	global_load_dword v173, v[18:19], off offset:64
; DI void transpose_w(const float* __restrict__ w, const float* __restrict__ rowscale, bf16_t* __restrict__ out, int K, int N, int bid, int nb, LAS float* tile) {
;     ...
;         for (int q = 0; q < 8; ++q) { const int t = t0 + q * nb; if (t < ntile) { const int k0 = (t % nkt) * 64, n0 = (t / nkt) * 32;
; #pragma unroll
;             for (int it = 0; it < 4; ++it) { const int i = it * 16 + (tid >> 5), j = tid & 31; v[q][it] = w[(size_t)(k0 + i) * N + n0 + j]; if (rowscale) v[q][it] *= rowscale[k0 + i]; } } }
.LBB0_37:
	v_or_b32_e32 v17, 32, v16
	v_mul_hi_i32_i24_e32 v57, 0x5880, v17
	v_mul_i32_i24_e32 v56, 0x5880, v17
	v_lshl_add_u64 v[56:57], v[14:15], 0, v[56:57]
	global_load_dword v42, v[56:57], off
	s_and_b64 vcc, exec, s[0:1]
	s_cbranch_vccnz .LBB0_39
	global_load_dword v174, v[18:19], off offset:128
.LBB0_39:
	v_add_u32_e32 v16, 48, v16
	v_mul_hi_i32_i24_e32 v17, 0x5880, v16
	v_mul_i32_i24_e32 v16, 0x5880, v16
	v_lshl_add_u64 v[14:15], v[14:15], 0, v[16:17]
	global_load_dword v49, v[14:15], off
	s_and_b64 vcc, exec, s[0:1]
	s_cbranch_vccnz .LBB0_41
	global_load_dword v175, v[18:19], off offset:192
.LBB0_41:
	s_add_i32 s87, s78, s83
	s_cmpk_lt_i32 s87, 0x1620
	s_cselect_b64 s[34:35], -1, 0
	s_cmpk_gt_i32 s87, 0x161f
	s_cbranch_scc1 .LBB0_50
	s_ashr_i32 s8, s87, 31
	s_lshr_b32 s8, s8, 27
	s_add_i32 s8, s87, s8
	s_andn2_b32 s8, s8, 31
	s_sub_i32 s9, s87, s8
	v_lshl_or_b32 v16, s9, 6, v3
	s_ashr_i32 s9, s8, 31
	v_lshl_add_u64 v[14:15], s[8:9], 2, v[12:13]
	v_mul_hi_i32_i24_e32 v19, 0x5880, v16
	v_mul_i32_i24_e32 v18, 0x5880, v16
	v_lshl_add_u64 v[18:19], v[14:15], 0, v[18:19]
	global_load_dword v27, v[18:19], off
	v_ashrrev_i32_e32 v17, 31, v16
	s_and_b64 vcc, exec, s[0:1]
	v_lshl_add_u64 v[18:19], v[16:17], 2, s[26:27]
	s_cbranch_vccnz .LBB0_44
	global_load_dword v176, v[18:19], off
.LBB0_44:
	v_add_u32_e32 v17, 16, v16
	v_mul_hi_i32_i24_e32 v57, 0x5880, v17
	v_mul_i32_i24_e32 v56, 0x5880, v17
	v_lshl_add_u64 v[56:57], v[14:15], 0, v[56:57]
	global_load_dword v34, v[56:57], off
	s_and_b64 vcc, exec, s[0:1]
	s_cbranch_vccnz .LBB0_46
	global_load_dword v177, v[18:19], off offset:64
.LBB0_46:
	v_or_b32_e32 v17, 32, v16
	v_mul_hi_i32_i24_e32 v57, 0x5880, v17
	v_mul_i32_i24_e32 v56, 0x5880, v17
	v_lshl_add_u64 v[56:57], v[14:15], 0, v[56:57]
	global_load_dword v41, v[56:57], off
	s_and_b64 vcc, exec, s[0:1]
	s_cbranch_vccnz .LBB0_48
	global_load_dword v178, v[18:19], off offset:128
.LBB0_48:
	v_add_u32_e32 v16, 48, v16
	v_mul_hi_i32_i24_e32 v17, 0x5880, v16
	v_mul_i32_i24_e32 v16, 0x5880, v16
	v_lshl_add_u64 v[14:15], v[14:15], 0, v[16:17]
	global_load_dword v48, v[14:15], off
	s_and_b64 vcc, exec, s[0:1]
	s_cbranch_vccnz .LBB0_50
	global_load_dword v179, v[18:19], off offset:192
.LBB0_50:
	s_add_i32 s88, s79, s83
	s_cmpk_lt_i32 s88, 0x1620
	s_cselect_b64 s[36:37], -1, 0
	s_cmpk_gt_i32 s88, 0x161f
	s_cbranch_scc1 .LBB0_59
	s_ashr_i32 s8, s88, 31
	s_lshr_b32 s8, s8, 27
	s_add_i32 s8, s88, s8
	s_andn2_b32 s8, s8, 31
	s_sub_i32 s9, s88, s8
	v_lshl_or_b32 v16, s9, 6, v3
	s_ashr_i32 s9, s8, 31
	v_lshl_add_u64 v[14:15], s[8:9], 2, v[12:13]
	v_mul_hi_i32_i24_e32 v19, 0x5880, v16
	v_mul_i32_i24_e32 v18, 0x5880, v16
	v_lshl_add_u64 v[18:19], v[14:15], 0, v[18:19]
	global_load_dword v26, v[18:19], off
	v_ashrrev_i32_e32 v17, 31, v16
	s_and_b64 vcc, exec, s[0:1]
	v_lshl_add_u64 v[18:19], v[16:17], 2, s[26:27]
	s_cbranch_vccnz .LBB0_53
	global_load_dword v180, v[18:19], off
.LBB0_53:
	v_add_u32_e32 v17, 16, v16
	v_mul_hi_i32_i24_e32 v57, 0x5880, v17
	v_mul_i32_i24_e32 v56, 0x5880, v17
	v_lshl_add_u64 v[56:57], v[14:15], 0, v[56:57]
	global_load_dword v33, v[56:57], off
	s_and_b64 vcc, exec, s[0:1]
	s_cbranch_vccnz .LBB0_55
	global_load_dword v181, v[18:19], off offset:64
.LBB0_55:
	v_or_b32_e32 v17, 32, v16
	v_mul_hi_i32_i24_e32 v57, 0x5880, v17
	v_mul_i32_i24_e32 v56, 0x5880, v17
	v_lshl_add_u64 v[56:57], v[14:15], 0, v[56:57]
	global_load_dword v40, v[56:57], off
	s_and_b64 vcc, exec, s[0:1]
	s_cbranch_vccnz .LBB0_57
	global_load_dword v182, v[18:19], off offset:128
.LBB0_57:
	v_add_u32_e32 v16, 48, v16
	v_mul_hi_i32_i24_e32 v17, 0x5880, v16
	v_mul_i32_i24_e32 v16, 0x5880, v16
	v_lshl_add_u64 v[14:15], v[14:15], 0, v[16:17]
	global_load_dword v47, v[14:15], off
	s_and_b64 vcc, exec, s[0:1]
	s_cbranch_vccnz .LBB0_59
	global_load_dword v183, v[18:19], off offset:192
; DI void transpose_w(const float* __restrict__ w, const float* __restrict__ rowscale, bf16_t* __restrict__ out, int K, int N, int bid, int nb, LAS float* tile) {
;     ...
;         for (int q = 0; q < 8; ++q) { const int t = t0 + q * nb; if (t < ntile) { const int k0 = (t % nkt) * 64, n0 = (t / nkt) * 32;
; #pragma unroll
;             for (int it = 0; it < 4; ++it) { const int i = it * 16 + (tid >> 5), j = tid & 31; v[q][it] = w[(size_t)(k0 + i) * N + n0 + j]; if (rowscale) v[q][it] *= rowscale[k0 + i]; } } }
.LBB0_59:
	s_add_i32 s89, s80, s83
	s_cmpk_lt_i32 s89, 0x1620
	s_cselect_b64 s[38:39], -1, 0
	s_cmpk_gt_i32 s89, 0x161f
	s_cbranch_scc1 .LBB0_68
	s_ashr_i32 s8, s89, 31
	s_lshr_b32 s8, s8, 27
	s_add_i32 s8, s89, s8
	s_andn2_b32 s8, s8, 31
	s_sub_i32 s9, s89, s8
	v_lshl_or_b32 v16, s9, 6, v3
	s_ashr_i32 s9, s8, 31
	v_lshl_add_u64 v[14:15], s[8:9], 2, v[12:13]
	v_mul_hi_i32_i24_e32 v19, 0x5880, v16
	v_mul_i32_i24_e32 v18, 0x5880, v16
	v_lshl_add_u64 v[18:19], v[14:15], 0, v[18:19]
	global_load_dword v25, v[18:19], off
	v_ashrrev_i32_e32 v17, 31, v16
	s_and_b64 vcc, exec, s[0:1]
	v_lshl_add_u64 v[18:19], v[16:17], 2, s[26:27]
	s_cbranch_vccnz .LBB0_62
	global_load_dword v184, v[18:19], off
.LBB0_62:
	v_add_u32_e32 v17, 16, v16
	v_mul_hi_i32_i24_e32 v57, 0x5880, v17
	v_mul_i32_i24_e32 v56, 0x5880, v17
	v_lshl_add_u64 v[56:57], v[14:15], 0, v[56:57]
	global_load_dword v31, v[56:57], off
	s_and_b64 vcc, exec, s[0:1]
	s_cbranch_vccnz .LBB0_64
	global_load_dword v185, v[18:19], off offset:64
.LBB0_64:
	v_or_b32_e32 v17, 32, v16
	v_mul_hi_i32_i24_e32 v57, 0x5880, v17
	v_mul_i32_i24_e32 v56, 0x5880, v17
	v_lshl_add_u64 v[56:57], v[14:15], 0, v[56:57]
	global_load_dword v38, v[56:57], off
	s_and_b64 vcc, exec, s[0:1]
	s_cbranch_vccnz .LBB0_66
	global_load_dword v186, v[18:19], off offset:128
.LBB0_66:
	v_add_u32_e32 v16, 48, v16
	v_mul_hi_i32_i24_e32 v17, 0x5880, v16
	v_mul_i32_i24_e32 v16, 0x5880, v16
	v_lshl_add_u64 v[14:15], v[14:15], 0, v[16:17]
	global_load_dword v45, v[14:15], off
	s_and_b64 vcc, exec, s[0:1]
	s_cbranch_vccnz .LBB0_68
	global_load_dword v187, v[18:19], off offset:192
.LBB0_68:
	s_add_i32 s90, s81, s83
	s_cmpk_lt_i32 s90, 0x1620
	s_cselect_b64 s[40:41], -1, 0
	s_cmpk_gt_i32 s90, 0x161f
	s_cbranch_scc1 .LBB0_77
	s_ashr_i32 s8, s90, 31
	s_lshr_b32 s8, s8, 27
	s_add_i32 s8, s90, s8
	s_andn2_b32 s8, s8, 31
	s_sub_i32 s9, s90, s8
	v_lshl_or_b32 v16, s9, 6, v3
	s_ashr_i32 s9, s8, 31
	v_lshl_add_u64 v[14:15], s[8:9], 2, v[12:13]
	v_mul_hi_i32_i24_e32 v19, 0x5880, v16
	v_mul_i32_i24_e32 v18, 0x5880, v16
	v_lshl_add_u64 v[18:19], v[14:15], 0, v[18:19]
	global_load_dword v23, v[18:19], off
	v_ashrrev_i32_e32 v17, 31, v16
	s_and_b64 vcc, exec, s[0:1]
	v_lshl_add_u64 v[18:19], v[16:17], 2, s[26:27]
	s_cbranch_vccnz .LBB0_71
	global_load_dword v188, v[18:19], off
.LBB0_71:
	v_add_u32_e32 v17, 16, v16
	v_mul_hi_i32_i24_e32 v57, 0x5880, v17
	v_mul_i32_i24_e32 v56, 0x5880, v17
	v_lshl_add_u64 v[56:57], v[14:15], 0, v[56:57]
	global_load_dword v29, v[56:57], off
	s_and_b64 vcc, exec, s[0:1]
	s_cbranch_vccnz .LBB0_73
	global_load_dword v189, v[18:19], off offset:64
.LBB0_73:
	v_or_b32_e32 v17, 32, v16
	v_mul_hi_i32_i24_e32 v57, 0x5880, v17
	v_mul_i32_i24_e32 v56, 0x5880, v17
	v_lshl_add_u64 v[56:57], v[14:15], 0, v[56:57]
	global_load_dword v36, v[56:57], off
	s_and_b64 vcc, exec, s[0:1]
	s_cbranch_vccnz .LBB0_75
	global_load_dword v190, v[18:19], off offset:128
.LBB0_75:
	v_add_u32_e32 v16, 48, v16
	v_mul_hi_i32_i24_e32 v17, 0x5880, v16
	v_mul_i32_i24_e32 v16, 0x5880, v16
	v_lshl_add_u64 v[14:15], v[14:15], 0, v[16:17]
	global_load_dword v43, v[14:15], off
	s_and_b64 vcc, exec, s[0:1]
	s_cbranch_vccnz .LBB0_77
	global_load_dword v191, v[18:19], off offset:192
.LBB0_77:
	s_and_b64 vcc, exec, s[0:1]
	s_cbranch_vccnz .Lp0_nonorm
	s_waitcnt vmcnt(0)
	v_mul_f32_e32 v6, v6, v160
	v_mul_f32_e32 v52, v52, v161
	v_mul_f32_e32 v53, v53, v162
	v_mul_f32_e32 v54, v54, v163
	v_mul_f32_e32 v32, v32, v164
	v_mul_f32_e32 v39, v39, v165
	v_mul_f32_e32 v46, v46, v166
	v_mul_f32_e32 v51, v51, v167
	v_mul_f32_e32 v30, v30, v168
	v_mul_f32_e32 v37, v37, v169
	v_mul_f32_e32 v44, v44, v170
	v_mul_f32_e32 v50, v50, v171
	v_mul_f32_e32 v28, v28, v172
	v_mul_f32_e32 v35, v35, v173
	v_mul_f32_e32 v42, v42, v174
	v_mul_f32_e32 v49, v49, v175
	v_mul_f32_e32 v27, v27, v176
	v_mul_f32_e32 v34, v34, v177
	v_mul_f32_e32 v41, v41, v178
	v_mul_f32_e32 v48, v48, v179
	v_mul_f32_e32 v26, v26, v180
	v_mul_f32_e32 v33, v33, v181
	v_mul_f32_e32 v40, v40, v182
	v_mul_f32_e32 v47, v47, v183
	v_mul_f32_e32 v25, v25, v184
	v_mul_f32_e32 v31, v31, v185
	v_mul_f32_e32 v38, v38, v186
	v_mul_f32_e32 v45, v45, v187
	v_mul_f32_e32 v23, v23, v188
	v_mul_f32_e32 v29, v29, v189
	v_mul_f32_e32 v36, v36, v190
	v_mul_f32_e32 v43, v43, v191
